# input-GEMM transposed epilogue: two LDS reads in flight per wait in the 4-step serialized read paths; on top of previous version
# speedup vs baseline: 1.0025x; 1.0006x over previous
; DI unsigned pk2(float lo, float hi) { f32x2 v = {lo, hi}; return __builtin_bit_cast(unsigned, __builtin_convertvector(v, bf16x2n)); }
;     DI void store(const f32x4 (&acc)[2][2][4][2], const pg8::Unit& u, int wr, int wc, int fr, int fq) const {
;     ...
;                         } else if (colt < 3072) {
;                             u32x4 o = {pk2(tc[8 * hs], tc[8 * hs + 1]), pk2(tc[8 * hs + 2], tc[8 * hs + 3]), pk2(tc[8 * hs + 4], tc[8 * hs + 5]), pk2(tc[8 * hs + 6], tc[8 * hs + 7])};
;                             *(u32x4*)(vta + (size_t)(col - 2048) * S + rowb + 8 * hs) = o;
.LBB0_357:
	s_andn2_b64 vcc, exec, s[22:23]
	s_cbranch_vccnz .LBB0_359
	ds_read2_b32 v[148:149], v168 offset1:1
	ds_read2_b32 v[162:163], v168 offset0:2 offset1:3
	s_ashr_i32 s21, s20, 31
	v_lshlrev_b32_e32 v152, 1, v138
	v_mov_b32_e32 v153, v97
	s_waitcnt lgkmcnt(0)
	v_cvt_pk_bf16_f32 v160, v148, v149
	v_cvt_pk_bf16_f32 v161, v162, v163
	ds_read2_b32 v[148:149], v168 offset0:4 offset1:5
	ds_read2_b32 v[162:163], v168 offset0:6 offset1:7
	s_waitcnt lgkmcnt(0)
	v_cvt_pk_bf16_f32 v163, v162, v163
	v_cvt_pk_bf16_f32 v162, v148, v149
	v_lshl_add_u64 v[148:149], s[4:5], 0, v[154:155]
	v_lshl_add_u64 v[148:149], s[20:21], 1, v[148:149]
	v_lshl_add_u64 v[148:149], v[148:149], 0, v[152:153]
	global_store_dwordx4 v[148:149], v[160:163], off

; DI unsigned pk2(float lo, float hi) { f32x2 v = {lo, hi}; return __builtin_bit_cast(unsigned, __builtin_convertvector(v, bf16x2n)); }
;     DI void store(const f32x4 (&acc)[2][2][4][2], const pg8::Unit& u, int wr, int wc, int fr, int fq) const {
;     ...
;                         } else if (kind == 3) {
;                             u32x4 o = {pk2(tc[4 * hs], tc[4 * hs + 1]), pk2(tc[4 * hs + 2], tc[4 * hs + 3]), pk2(tc[8 + 4 * hs], tc[9 + 4 * hs]), pk2(tc[10 + 4 * hs], tc[11 + 4 * hs])};
;                             *(u32x4*)(vtc + (size_t)(col - (C_CQKV + 2048)) * S + rowb + 8 * hs) = o;
.LBB0_360:
	s_andn2_b64 vcc, exec, s[22:23]
	s_cbranch_vccnz .LBB0_362
	ds_read2_b32 v[148:149], v169 offset1:1
	ds_read2_b32 v[162:163], v169 offset0:2 offset1:3
	s_ashr_i32 s21, s20, 31
	v_lshlrev_b32_e32 v152, 1, v138
	v_mov_b32_e32 v153, v97
	s_waitcnt lgkmcnt(0)
	v_cvt_pk_bf16_f32 v160, v148, v149
	v_cvt_pk_bf16_f32 v161, v162, v163
	ds_read2_b32 v[148:149], v169 offset0:8 offset1:9
	ds_read2_b32 v[162:163], v169 offset0:10 offset1:11
	s_waitcnt lgkmcnt(0)
	v_cvt_pk_bf16_f32 v163, v162, v163
	v_cvt_pk_bf16_f32 v162, v148, v149
	v_lshl_add_u64 v[148:149], s[6:7], 0, v[150:151]
	v_lshl_add_u64 v[148:149], s[20:21], 1, v[148:149]
	v_lshl_add_u64 v[148:149], v[148:149], 0, v[152:153]
	global_store_dwordx4 v[148:149], v[160:163], off

; DI unsigned pk2(float lo, float hi) { f32x2 v = {lo, hi}; return __builtin_bit_cast(unsigned, __builtin_convertvector(v, bf16x2n)); }
;     DI void store(const f32x4 (&acc)[2][2][4][2], const pg8::Unit& u, int wr, int wc, int fr, int fq) const {
;     ...
;                         } else if (colt < 3072) {
;                             u32x4 o = {pk2(tc[8 * hs], tc[8 * hs + 1]), pk2(tc[8 * hs + 2], tc[8 * hs + 3]), pk2(tc[8 * hs + 4], tc[8 * hs + 5]), pk2(tc[8 * hs + 6], tc[8 * hs + 7])};
;                             *(u32x4*)(vta + (size_t)(col - 2048) * S + rowb + 8 * hs) = o;
.LBB0_369:
	s_andn2_b64 vcc, exec, s[24:25]
	s_cbranch_vccnz .LBB0_371
	ds_read2_b32 v[152:153], v168 offset1:1
	ds_read2_b32 v[176:177], v168 offset0:2 offset1:3
	s_ashr_i32 s23, s22, 31
	v_lshlrev_b32_e32 v156, 1, v138
	v_mov_b32_e32 v157, v97
	s_waitcnt lgkmcnt(0)
	v_cvt_pk_bf16_f32 v174, v152, v153
	v_cvt_pk_bf16_f32 v175, v176, v177
	ds_read2_b32 v[152:153], v168 offset0:4 offset1:5
	ds_read2_b32 v[176:177], v168 offset0:6 offset1:7
	s_waitcnt lgkmcnt(0)
	v_cvt_pk_bf16_f32 v177, v176, v177
	v_cvt_pk_bf16_f32 v176, v152, v153
	v_lshl_add_u64 v[152:153], s[4:5], 0, v[154:155]
	v_lshl_add_u64 v[152:153], s[22:23], 1, v[152:153]
	v_lshl_add_u64 v[152:153], v[152:153], 0, v[156:157]
	global_store_dwordx4 v[152:153], v[174:177], off

; DI unsigned pk2(float lo, float hi) { f32x2 v = {lo, hi}; return __builtin_bit_cast(unsigned, __builtin_convertvector(v, bf16x2n)); }
;     DI void store(const f32x4 (&acc)[2][2][4][2], const pg8::Unit& u, int wr, int wc, int fr, int fq) const {
;     ...
;                         } else if (kind == 3) {
;                             u32x4 o = {pk2(tc[4 * hs], tc[4 * hs + 1]), pk2(tc[4 * hs + 2], tc[4 * hs + 3]), pk2(tc[8 + 4 * hs], tc[9 + 4 * hs]), pk2(tc[10 + 4 * hs], tc[11 + 4 * hs])};
;                             *(u32x4*)(vtc + (size_t)(col - (C_CQKV + 2048)) * S + rowb + 8 * hs) = o;
.LBB0_372:
	s_andn2_b64 vcc, exec, s[24:25]
	s_cbranch_vccnz .LBB0_374
	ds_read2_b32 v[152:153], v169 offset1:1
	ds_read2_b32 v[176:177], v169 offset0:2 offset1:3
	s_ashr_i32 s23, s22, 31
	v_lshlrev_b32_e32 v156, 1, v138
	v_mov_b32_e32 v157, v97
	s_waitcnt lgkmcnt(0)
	v_cvt_pk_bf16_f32 v174, v152, v153
	v_cvt_pk_bf16_f32 v175, v176, v177
	ds_read2_b32 v[152:153], v169 offset0:8 offset1:9
	ds_read2_b32 v[176:177], v169 offset0:10 offset1:11
	s_waitcnt lgkmcnt(0)
	v_cvt_pk_bf16_f32 v177, v176, v177
	v_cvt_pk_bf16_f32 v176, v152, v153
	v_lshl_add_u64 v[152:153], s[6:7], 0, v[150:151]
	v_lshl_add_u64 v[152:153], s[22:23], 1, v[152:153]
	v_lshl_add_u64 v[152:153], v[152:153], 0, v[156:157]
	global_store_dwordx4 v[152:153], v[174:177], off

; DI unsigned pk2(float lo, float hi) { f32x2 v = {lo, hi}; return __builtin_bit_cast(unsigned, __builtin_convertvector(v, bf16x2n)); }
;     DI void store(const f32x4 (&acc)[2][2][4][2], const pg8::Unit& u, int wr, int wc, int fr, int fq) const {
;     ...
;                         } else if (colt < 3072) {
;                             u32x4 o = {pk2(tc[8 * hs], tc[8 * hs + 1]), pk2(tc[8 * hs + 2], tc[8 * hs + 3]), pk2(tc[8 * hs + 4], tc[8 * hs + 5]), pk2(tc[8 * hs + 6], tc[8 * hs + 7])};
;                             *(u32x4*)(vta + (size_t)(col - 2048) * S + rowb + 8 * hs) = o;
.LBB0_381:
	s_andn2_b64 vcc, exec, s[26:27]
	s_cbranch_vccnz .LBB0_383
	ds_read2_b32 v[152:153], v168 offset1:1
	ds_read2_b32 v[176:177], v168 offset0:2 offset1:3
	s_ashr_i32 s25, s24, 31
	v_lshlrev_b32_e32 v156, 1, v138
	v_mov_b32_e32 v157, v97
	s_waitcnt lgkmcnt(0)
	v_cvt_pk_bf16_f32 v174, v152, v153
	v_cvt_pk_bf16_f32 v175, v176, v177
	ds_read2_b32 v[152:153], v168 offset0:4 offset1:5
	ds_read2_b32 v[176:177], v168 offset0:6 offset1:7
	s_waitcnt lgkmcnt(0)
	v_cvt_pk_bf16_f32 v177, v176, v177
	v_cvt_pk_bf16_f32 v176, v152, v153
	v_lshl_add_u64 v[152:153], s[4:5], 0, v[154:155]
	v_lshl_add_u64 v[152:153], s[24:25], 1, v[152:153]
	v_lshl_add_u64 v[152:153], v[152:153], 0, v[156:157]
	global_store_dwordx4 v[152:153], v[174:177], off

; DI unsigned pk2(float lo, float hi) { f32x2 v = {lo, hi}; return __builtin_bit_cast(unsigned, __builtin_convertvector(v, bf16x2n)); }
;     DI void store(const f32x4 (&acc)[2][2][4][2], const pg8::Unit& u, int wr, int wc, int fr, int fq) const {
;     ...
;                         } else if (kind == 3) {
;                             u32x4 o = {pk2(tc[4 * hs], tc[4 * hs + 1]), pk2(tc[4 * hs + 2], tc[4 * hs + 3]), pk2(tc[8 + 4 * hs], tc[9 + 4 * hs]), pk2(tc[10 + 4 * hs], tc[11 + 4 * hs])};
;                             *(u32x4*)(vtc + (size_t)(col - (C_CQKV + 2048)) * S + rowb + 8 * hs) = o;
.LBB0_384:
	s_andn2_b64 vcc, exec, s[26:27]
	s_cbranch_vccnz .LBB0_386
	ds_read2_b32 v[152:153], v169 offset1:1
	ds_read2_b32 v[176:177], v169 offset0:2 offset1:3
	s_ashr_i32 s25, s24, 31
	v_lshlrev_b32_e32 v156, 1, v138
	v_mov_b32_e32 v157, v97
	s_waitcnt lgkmcnt(0)
	v_cvt_pk_bf16_f32 v174, v152, v153
	v_cvt_pk_bf16_f32 v175, v176, v177
	ds_read2_b32 v[152:153], v169 offset0:8 offset1:9
	ds_read2_b32 v[176:177], v169 offset0:10 offset1:11
	s_waitcnt lgkmcnt(0)
	v_cvt_pk_bf16_f32 v177, v176, v177
	v_cvt_pk_bf16_f32 v176, v152, v153
	v_lshl_add_u64 v[152:153], s[6:7], 0, v[150:151]
	v_lshl_add_u64 v[152:153], s[24:25], 1, v[152:153]
	v_lshl_add_u64 v[152:153], v[152:153], 0, v[156:157]
	global_store_dwordx4 v[152:153], v[174:177], off

; DI unsigned pk2(float lo, float hi) { f32x2 v = {lo, hi}; return __builtin_bit_cast(unsigned, __builtin_convertvector(v, bf16x2n)); }
;     DI void store(const f32x4 (&acc)[2][2][4][2], const pg8::Unit& u, int wr, int wc, int fr, int fq) const {
;     ...
;                         } else if (colt < 3072) {
;                             u32x4 o = {pk2(tc[8 * hs], tc[8 * hs + 1]), pk2(tc[8 * hs + 2], tc[8 * hs + 3]), pk2(tc[8 * hs + 4], tc[8 * hs + 5]), pk2(tc[8 * hs + 6], tc[8 * hs + 7])};
;                             *(u32x4*)(vta + (size_t)(col - 2048) * S + rowb + 8 * hs) = o;
.LBB0_393:
	s_andn2_b64 vcc, exec, s[50:51]
	s_cbranch_vccnz .LBB0_395
	ds_read2_b32 v[152:153], v168 offset1:1
	ds_read2_b32 v[176:177], v168 offset0:2 offset1:3
	s_ashr_i32 s27, s26, 31
	v_lshlrev_b32_e32 v156, 1, v138
	v_mov_b32_e32 v157, v97
	s_waitcnt lgkmcnt(0)
	v_cvt_pk_bf16_f32 v174, v152, v153
	v_cvt_pk_bf16_f32 v175, v176, v177
	ds_read2_b32 v[152:153], v168 offset0:4 offset1:5
	ds_read2_b32 v[176:177], v168 offset0:6 offset1:7
	s_waitcnt lgkmcnt(0)
	v_cvt_pk_bf16_f32 v177, v176, v177
	v_cvt_pk_bf16_f32 v176, v152, v153
	v_lshl_add_u64 v[152:153], s[4:5], 0, v[154:155]
	v_lshl_add_u64 v[152:153], s[26:27], 1, v[152:153]
	v_lshl_add_u64 v[152:153], v[152:153], 0, v[156:157]
	global_store_dwordx4 v[152:153], v[174:177], off

; DI unsigned pk2(float lo, float hi) { f32x2 v = {lo, hi}; return __builtin_bit_cast(unsigned, __builtin_convertvector(v, bf16x2n)); }
;     DI void store(const f32x4 (&acc)[2][2][4][2], const pg8::Unit& u, int wr, int wc, int fr, int fq) const {
;     ...
;                             u32x4 o = {pk2(tc[4 * hs], tc[4 * hs + 1]), pk2(tc[4 * hs + 2], tc[4 * hs + 3]), pk2(tc[8 + 4 * hs], tc[9 + 4 * hs]), pk2(tc[10 + 4 * hs], tc[11 + 4 * hs])};
;                             *(u32x4*)(vtc + (size_t)(col - (C_CQKV + 2048)) * S + rowb + 8 * hs) = o;
.LBB0_396:
	s_andn2_b64 vcc, exec, s[50:51]
	s_cbranch_vccnz .LBB0_398
	ds_read2_b32 v[152:153], v169 offset1:1
	ds_read2_b32 v[176:177], v169 offset0:2 offset1:3
	s_ashr_i32 s27, s26, 31
	v_lshlrev_b32_e32 v156, 1, v138
	v_mov_b32_e32 v157, v97
	s_waitcnt lgkmcnt(0)
	v_cvt_pk_bf16_f32 v174, v152, v153
	v_cvt_pk_bf16_f32 v175, v176, v177
	ds_read2_b32 v[152:153], v169 offset0:8 offset1:9
	ds_read2_b32 v[176:177], v169 offset0:10 offset1:11
	s_waitcnt lgkmcnt(0)
	v_cvt_pk_bf16_f32 v177, v176, v177
	v_cvt_pk_bf16_f32 v176, v152, v153
	v_lshl_add_u64 v[152:153], s[6:7], 0, v[150:151]
	v_lshl_add_u64 v[152:153], s[26:27], 1, v[152:153]
	v_lshl_add_u64 v[152:153], v[152:153], 0, v[156:157]
	global_store_dwordx4 v[152:153], v[174:177], off

; DI unsigned pk2(float lo, float hi) { f32x2 v = {lo, hi}; return __builtin_bit_cast(unsigned, __builtin_convertvector(v, bf16x2n)); }
;     DI void store(const f32x4 (&acc)[2][2][4][2], const pg8::Unit& u, int wr, int wc, int fr, int fq) const {
;     ...
;                             u32x4 o = {pk2(tc[8 * hs], tc[8 * hs + 1]), pk2(tc[8 * hs + 2], tc[8 * hs + 3]), pk2(tc[8 * hs + 4], tc[8 * hs + 5]), pk2(tc[8 * hs + 6], tc[8 * hs + 7])};
;                             *(u32x4*)(vta + (size_t)(col - 2048) * S + rowb + 8 * hs) = o;
.LBB0_489:
	s_andn2_b64 vcc, exec, s[50:51]
	s_cbranch_vccnz .LBB0_491
	ds_read2_b32 v[158:159], v168 offset1:1
	ds_read2_b32 v[176:177], v168 offset0:2 offset1:3
	v_lshl_add_u64 v[154:155], s[4:5], 0, v[154:155]
	s_ashr_i32 s21, s20, 31
	v_lshl_add_u64 v[154:155], s[20:21], 1, v[154:155]
	s_waitcnt lgkmcnt(0)
	v_cvt_pk_bf16_f32 v174, v158, v159
	v_cvt_pk_bf16_f32 v175, v176, v177
	ds_read2_b32 v[158:159], v168 offset0:4 offset1:5
	ds_read2_b32 v[176:177], v168 offset0:6 offset1:7
	s_waitcnt lgkmcnt(0)
	v_cvt_pk_bf16_f32 v177, v176, v177
	v_cvt_pk_bf16_f32 v176, v158, v159
	v_lshlrev_b32_e32 v158, 1, v138
	v_mov_b32_e32 v159, v97
	v_lshl_add_u64 v[154:155], v[154:155], 0, v[158:159]
	global_store_dwordx4 v[154:155], v[174:177], off

; DI unsigned pk2(float lo, float hi) { f32x2 v = {lo, hi}; return __builtin_bit_cast(unsigned, __builtin_convertvector(v, bf16x2n)); }
;     DI void store(const f32x4 (&acc)[2][2][4][2], const pg8::Unit& u, int wr, int wc, int fr, int fq) const {
;     ...
;                             u32x4 o = {pk2(tc[4 * hs], tc[4 * hs + 1]), pk2(tc[4 * hs + 2], tc[4 * hs + 3]), pk2(tc[8 + 4 * hs], tc[9 + 4 * hs]), pk2(tc[10 + 4 * hs], tc[11 + 4 * hs])};
;                             *(u32x4*)(vtc + (size_t)(col - (C_CQKV + 2048)) * S + rowb + 8 * hs) = o;
.LBB0_492:
	s_andn2_b64 vcc, exec, s[50:51]
	s_cbranch_vccnz .LBB0_494
	ds_read2_b32 v[154:155], v169 offset1:1
	ds_read2_b32 v[176:177], v169 offset0:2 offset1:3
	v_lshl_add_u64 v[150:151], s[6:7], 0, v[150:151]
	s_ashr_i32 s21, s20, 31
	v_lshl_add_u64 v[150:151], s[20:21], 1, v[150:151]
	s_waitcnt lgkmcnt(0)
	v_cvt_pk_bf16_f32 v174, v154, v155
	v_cvt_pk_bf16_f32 v175, v176, v177
	ds_read2_b32 v[154:155], v169 offset0:8 offset1:9
	ds_read2_b32 v[176:177], v169 offset0:10 offset1:11
	s_waitcnt lgkmcnt(0)
	v_cvt_pk_bf16_f32 v177, v176, v177
	v_cvt_pk_bf16_f32 v176, v154, v155
	v_lshlrev_b32_e32 v154, 1, v138
	v_mov_b32_e32 v155, v97
	v_lshl_add_u64 v[150:151], v[150:151], 0, v[154:155]
	global_store_dwordx4 v[150:151], v[174:177], off

; DI unsigned pk2(float lo, float hi) { f32x2 v = {lo, hi}; return __builtin_bit_cast(unsigned, __builtin_convertvector(v, bf16x2n)); }
;     DI void store(const f32x4 (&acc)[2][2][4][2], const pg8::Unit& u, int wr, int wc, int fr, int fq) const {
;     ...
;                             u32x4 o = {pk2(tc[8 * hs], tc[8 * hs + 1]), pk2(tc[8 * hs + 2], tc[8 * hs + 3]), pk2(tc[8 * hs + 4], tc[8 * hs + 5]), pk2(tc[8 * hs + 6], tc[8 * hs + 7])};
;                             *(u32x4*)(vta + (size_t)(col - 2048) * S + rowb + 8 * hs) = o;
.LBB0_501:
	s_andn2_b64 vcc, exec, s[50:51]
	s_cbranch_vccnz .LBB0_503
	ds_read2_b32 v[150:151], v168 offset1:1
	ds_read2_b32 v[176:177], v168 offset0:2 offset1:3
	s_ashr_i32 s23, s22, 31
	v_lshlrev_b32_e32 v154, 1, v138
	v_mov_b32_e32 v155, v97
	s_waitcnt lgkmcnt(0)
	v_cvt_pk_bf16_f32 v174, v150, v151
	v_cvt_pk_bf16_f32 v175, v176, v177
	ds_read2_b32 v[150:151], v168 offset0:4 offset1:5
	ds_read2_b32 v[176:177], v168 offset0:6 offset1:7
	s_waitcnt lgkmcnt(0)
	v_cvt_pk_bf16_f32 v177, v176, v177
	v_cvt_pk_bf16_f32 v176, v150, v151
	v_lshl_add_u64 v[150:151], s[4:5], 0, v[156:157]
	v_lshl_add_u64 v[150:151], s[22:23], 1, v[150:151]
	v_lshl_add_u64 v[150:151], v[150:151], 0, v[154:155]
	global_store_dwordx4 v[150:151], v[174:177], off

; DI unsigned pk2(float lo, float hi) { f32x2 v = {lo, hi}; return __builtin_bit_cast(unsigned, __builtin_convertvector(v, bf16x2n)); }
;     DI void store(const f32x4 (&acc)[2][2][4][2], const pg8::Unit& u, int wr, int wc, int fr, int fq) const {
;     ...
;                             u32x4 o = {pk2(tc[4 * hs], tc[4 * hs + 1]), pk2(tc[4 * hs + 2], tc[4 * hs + 3]), pk2(tc[8 + 4 * hs], tc[9 + 4 * hs]), pk2(tc[10 + 4 * hs], tc[11 + 4 * hs])};
;                             *(u32x4*)(vtc + (size_t)(col - (C_CQKV + 2048)) * S + rowb + 8 * hs) = o;
.LBB0_504:
	s_andn2_b64 vcc, exec, s[50:51]
	s_cbranch_vccnz .LBB0_506
	ds_read2_b32 v[150:151], v169 offset1:1
	ds_read2_b32 v[176:177], v169 offset0:2 offset1:3
	s_ashr_i32 s23, s22, 31
	v_lshlrev_b32_e32 v154, 1, v138
	v_mov_b32_e32 v155, v97
	s_waitcnt lgkmcnt(0)
	v_cvt_pk_bf16_f32 v174, v150, v151
	v_cvt_pk_bf16_f32 v175, v176, v177
	ds_read2_b32 v[150:151], v169 offset0:8 offset1:9
	ds_read2_b32 v[176:177], v169 offset0:10 offset1:11
	s_waitcnt lgkmcnt(0)
	v_cvt_pk_bf16_f32 v177, v176, v177
	v_cvt_pk_bf16_f32 v176, v150, v151
	v_lshl_add_u64 v[150:151], s[6:7], 0, v[152:153]
	v_lshl_add_u64 v[150:151], s[22:23], 1, v[150:151]
	v_lshl_add_u64 v[150:151], v[150:151], 0, v[154:155]
	global_store_dwordx4 v[150:151], v[174:177], off

; DI unsigned pk2(float lo, float hi) { f32x2 v = {lo, hi}; return __builtin_bit_cast(unsigned, __builtin_convertvector(v, bf16x2n)); }
;     DI void store(const f32x4 (&acc)[2][2][4][2], const pg8::Unit& u, int wr, int wc, int fr, int fq) const {
;     ...
;                             u32x4 o = {pk2(tc[8 * hs], tc[8 * hs + 1]), pk2(tc[8 * hs + 2], tc[8 * hs + 3]), pk2(tc[8 * hs + 4], tc[8 * hs + 5]), pk2(tc[8 * hs + 6], tc[8 * hs + 7])};
;                             *(u32x4*)(vta + (size_t)(col - 2048) * S + rowb + 8 * hs) = o;
.LBB0_513:
	s_andn2_b64 vcc, exec, s[22:23]
	s_cbranch_vccnz .LBB0_515
	ds_read2_b32 v[150:151], v168 offset1:1
	ds_read2_b32 v[176:177], v168 offset0:2 offset1:3
	s_ashr_i32 s25, s24, 31
	v_lshlrev_b32_e32 v154, 1, v138
	v_mov_b32_e32 v155, v97
	s_waitcnt lgkmcnt(0)
	v_cvt_pk_bf16_f32 v174, v150, v151
	v_cvt_pk_bf16_f32 v175, v176, v177
	ds_read2_b32 v[150:151], v168 offset0:4 offset1:5
	ds_read2_b32 v[176:177], v168 offset0:6 offset1:7
	s_waitcnt lgkmcnt(0)
	v_cvt_pk_bf16_f32 v177, v176, v177
	v_cvt_pk_bf16_f32 v176, v150, v151
	v_lshl_add_u64 v[150:151], s[4:5], 0, v[156:157]
	v_lshl_add_u64 v[150:151], s[24:25], 1, v[150:151]
	v_lshl_add_u64 v[150:151], v[150:151], 0, v[154:155]
	global_store_dwordx4 v[150:151], v[174:177], off

; DI unsigned pk2(float lo, float hi) { f32x2 v = {lo, hi}; return __builtin_bit_cast(unsigned, __builtin_convertvector(v, bf16x2n)); }
;     DI void store(const f32x4 (&acc)[2][2][4][2], const pg8::Unit& u, int wr, int wc, int fr, int fq) const {
;     ...
;                             u32x4 o = {pk2(tc[4 * hs], tc[4 * hs + 1]), pk2(tc[4 * hs + 2], tc[4 * hs + 3]), pk2(tc[8 + 4 * hs], tc[9 + 4 * hs]), pk2(tc[10 + 4 * hs], tc[11 + 4 * hs])};
;                             *(u32x4*)(vtc + (size_t)(col - (C_CQKV + 2048)) * S + rowb + 8 * hs) = o;
.LBB0_516:
	s_andn2_b64 vcc, exec, s[22:23]
	s_cbranch_vccnz .LBB0_518
	ds_read2_b32 v[150:151], v169 offset1:1
	ds_read2_b32 v[176:177], v169 offset0:2 offset1:3
	s_ashr_i32 s25, s24, 31
	v_lshlrev_b32_e32 v154, 1, v138
	v_mov_b32_e32 v155, v97
	s_waitcnt lgkmcnt(0)
	v_cvt_pk_bf16_f32 v174, v150, v151
	v_cvt_pk_bf16_f32 v175, v176, v177
	ds_read2_b32 v[150:151], v169 offset0:8 offset1:9
	ds_read2_b32 v[176:177], v169 offset0:10 offset1:11
	s_waitcnt lgkmcnt(0)
	v_cvt_pk_bf16_f32 v177, v176, v177
	v_cvt_pk_bf16_f32 v176, v150, v151
	v_lshl_add_u64 v[150:151], s[6:7], 0, v[152:153]
	v_lshl_add_u64 v[150:151], s[24:25], 1, v[150:151]
	v_lshl_add_u64 v[150:151], v[150:151], 0, v[154:155]
	global_store_dwordx4 v[150:151], v[174:177], off

; DI unsigned pk2(float lo, float hi) { f32x2 v = {lo, hi}; return __builtin_bit_cast(unsigned, __builtin_convertvector(v, bf16x2n)); }
;     DI void store(const f32x4 (&acc)[2][2][4][2], const pg8::Unit& u, int wr, int wc, int fr, int fq) const {
;     ...
;                             u32x4 o = {pk2(tc[8 * hs], tc[8 * hs + 1]), pk2(tc[8 * hs + 2], tc[8 * hs + 3]), pk2(tc[8 * hs + 4], tc[8 * hs + 5]), pk2(tc[8 * hs + 6], tc[8 * hs + 7])};
;                             *(u32x4*)(vta + (size_t)(col - 2048) * S + rowb + 8 * hs) = o;
.LBB0_525:
	s_andn2_b64 vcc, exec, s[22:23]
	s_cbranch_vccnz .LBB0_527
	ds_read2_b32 v[150:151], v168 offset1:1
	ds_read2_b32 v[176:177], v168 offset0:2 offset1:3
	s_ashr_i32 s27, s26, 31
	v_lshlrev_b32_e32 v154, 1, v138
	v_mov_b32_e32 v155, v97
	s_waitcnt lgkmcnt(0)
	v_cvt_pk_bf16_f32 v174, v150, v151
	v_cvt_pk_bf16_f32 v175, v176, v177
	ds_read2_b32 v[150:151], v168 offset0:4 offset1:5
	ds_read2_b32 v[176:177], v168 offset0:6 offset1:7
	s_waitcnt lgkmcnt(0)
	v_cvt_pk_bf16_f32 v177, v176, v177
	v_cvt_pk_bf16_f32 v176, v150, v151
	v_lshl_add_u64 v[150:151], s[4:5], 0, v[156:157]
	v_lshl_add_u64 v[150:151], s[26:27], 1, v[150:151]
	v_lshl_add_u64 v[150:151], v[150:151], 0, v[154:155]
	global_store_dwordx4 v[150:151], v[174:177], off

; DI unsigned pk2(float lo, float hi) { f32x2 v = {lo, hi}; return __builtin_bit_cast(unsigned, __builtin_convertvector(v, bf16x2n)); }
;     DI void store(const f32x4 (&acc)[2][2][4][2], const pg8::Unit& u, int wr, int wc, int fr, int fq) const {
;     ...
;                             u32x4 o = {pk2(tc[4 * hs], tc[4 * hs + 1]), pk2(tc[4 * hs + 2], tc[4 * hs + 3]), pk2(tc[8 + 4 * hs], tc[9 + 4 * hs]), pk2(tc[10 + 4 * hs], tc[11 + 4 * hs])};
;                             *(u32x4*)(vtc + (size_t)(col - (C_CQKV + 2048)) * S + rowb + 8 * hs) = o;
.LBB0_528:
	s_andn2_b64 vcc, exec, s[22:23]
	s_cbranch_vccnz .LBB0_530
	ds_read2_b32 v[150:151], v169 offset1:1
	ds_read2_b32 v[176:177], v169 offset0:2 offset1:3
	s_ashr_i32 s27, s26, 31
	v_lshlrev_b32_e32 v154, 1, v138
	v_mov_b32_e32 v155, v97
	s_waitcnt lgkmcnt(0)
	v_cvt_pk_bf16_f32 v174, v150, v151
	v_cvt_pk_bf16_f32 v175, v176, v177
	ds_read2_b32 v[150:151], v169 offset0:8 offset1:9
	ds_read2_b32 v[176:177], v169 offset0:10 offset1:11
	s_waitcnt lgkmcnt(0)
	v_cvt_pk_bf16_f32 v177, v176, v177
	v_cvt_pk_bf16_f32 v176, v150, v151
	v_lshl_add_u64 v[150:151], s[6:7], 0, v[152:153]
	v_lshl_add_u64 v[150:151], s[26:27], 1, v[150:151]
	v_lshl_add_u64 v[150:151], v[150:151], 0, v[154:155]
	global_store_dwordx4 v[150:151], v[174:177], off

; DI unsigned pk2(float lo, float hi) { f32x2 v = {lo, hi}; return __builtin_bit_cast(unsigned, __builtin_convertvector(v, bf16x2n)); }
;     DI void store(const f32x4 (&acc)[2][2][4][2], const pg8::Unit& u, int wr, int wc, int fr, int fq) const {
;     ...
;                             u32x4 o = {pk2(tc[8 * hs], tc[8 * hs + 1]), pk2(tc[8 * hs + 2], tc[8 * hs + 3]), pk2(tc[8 * hs + 4], tc[8 * hs + 5]), pk2(tc[8 * hs + 6], tc[8 * hs + 7])};
;                             *(u32x4*)(vta + (size_t)(col - 2048) * S + rowb + 8 * hs) = o;
.LBB0_537:
	s_andn2_b64 vcc, exec, s[22:23]
	s_cbranch_vccnz .LBB0_539
	ds_read2_b32 v[150:151], v168 offset1:1
	ds_read2_b32 v[160:161], v168 offset0:2 offset1:3
	s_ashr_i32 s21, s20, 31
	v_lshlrev_b32_e32 v154, 1, v138
	v_mov_b32_e32 v155, v97
	s_waitcnt lgkmcnt(0)
	v_cvt_pk_bf16_f32 v158, v150, v151
	v_cvt_pk_bf16_f32 v159, v160, v161
	ds_read2_b32 v[150:151], v168 offset0:4 offset1:5
	ds_read2_b32 v[160:161], v168 offset0:6 offset1:7
	s_waitcnt lgkmcnt(0)
	v_cvt_pk_bf16_f32 v161, v160, v161
	v_cvt_pk_bf16_f32 v160, v150, v151
	v_lshl_add_u64 v[150:151], s[4:5], 0, v[156:157]
	v_lshl_add_u64 v[150:151], s[20:21], 1, v[150:151]
	v_lshl_add_u64 v[150:151], v[150:151], 0, v[154:155]
	global_store_dwordx4 v[150:151], v[158:161], off

; DI unsigned pk2(float lo, float hi) { f32x2 v = {lo, hi}; return __builtin_bit_cast(unsigned, __builtin_convertvector(v, bf16x2n)); }
;     DI void store(const f32x4 (&acc)[2][2][4][2], const pg8::Unit& u, int wr, int wc, int fr, int fq) const {
;     ...
;                             u32x4 o = {pk2(tc[4 * hs], tc[4 * hs + 1]), pk2(tc[4 * hs + 2], tc[4 * hs + 3]), pk2(tc[8 + 4 * hs], tc[9 + 4 * hs]), pk2(tc[10 + 4 * hs], tc[11 + 4 * hs])};
;                             *(u32x4*)(vtc + (size_t)(col - (C_CQKV + 2048)) * S + rowb + 8 * hs) = o;
.LBB0_540:
	s_andn2_b64 vcc, exec, s[22:23]
	s_cbranch_vccnz .LBB0_542
	ds_read2_b32 v[150:151], v169 offset1:1
	ds_read2_b32 v[156:157], v169 offset0:2 offset1:3
	s_ashr_i32 s21, s20, 31
	s_waitcnt lgkmcnt(0)
	v_cvt_pk_bf16_f32 v154, v150, v151
	v_cvt_pk_bf16_f32 v155, v156, v157
	ds_read2_b32 v[150:151], v169 offset0:8 offset1:9
	ds_read2_b32 v[156:157], v169 offset0:10 offset1:11
	s_waitcnt lgkmcnt(0)
	v_cvt_pk_bf16_f32 v157, v156, v157
	v_cvt_pk_bf16_f32 v156, v150, v151
	v_lshl_add_u64 v[150:151], s[6:7], 0, v[152:153]
	v_lshl_add_u64 v[150:151], s[20:21], 1, v[150:151]
	v_lshlrev_b32_e32 v152, 1, v138
	v_mov_b32_e32 v153, v97
	v_lshl_add_u64 v[150:151], v[150:151], 0, v[152:153]
	global_store_dwordx4 v[150:151], v[154:157], off
